# RWKV phase A triangular solve: M1-row LDS reads issued ahead (12 in flight) into fresh registers with counted waits (on v50)
# speedup vs baseline: 1.0105x; 1.0010x over previous
; #define LAS __attribute__((address_space(3)))
; __device__ __forceinline__ void rwkv_phaseA(const Ctx& F, LAS unsigned char* W, unsigned char* X, int b, int h, int c) {
;     ...
;     {
;         const int tc = lane & 31;
;         float x[32];
;         x[31] = (tc == 31) ? 1.f : 0.f;
; #pragma unroll
;         for (int s = 30; s >= 0; --s) {
;             float acc = 0.f;
; #pragma unroll
;             for (int j4 = (s + 1) / 4; j4 < 8; ++j4) { const f32x4 mrow = *(const LAS f32x4*)(W + RA_ZLO + (s * 32 + 4 * j4) * 4);
; #pragma unroll
;                 for (int e = 0; e < 4; ++e) if (4 * j4 + e > s) acc += mrow[e] * x[4 * j4 + e]; }
;             x[s] = (s == tc) ? 1.f : ((s < tc) ? -acc : 0.f);
;             asm volatile("" : "+v"(x[s]) :: "memory");
;         }
.LBB0_825:
	s_waitcnt lgkmcnt(0)
	v_mov_b32_e32 v0, s43
	ds_read_b128 v[152:155], v0 offset:3952
	ds_read_b64 v[150:151], v0 offset:3832
	ds_read_b128 v[156:159], v0 offset:3696
	ds_read_b128 v[160:163], v0 offset:3568
	ds_read_b128 v[164:167], v0 offset:3424
	ds_read_b128 v[168:171], v0 offset:3440
	ds_read_b64 v[172:173], v0 offset:3304
	ds_read_b128 v[176:179], v0 offset:3312
	ds_read_b128 v[180:183], v0 offset:3168
	ds_read_b128 v[184:187], v0 offset:3184
	ds_read_b128 v[188:191], v0 offset:3040
	ds_read_b128 v[192:195], v0 offset:3056
	s_nop 0
	v_and_b32_e32 v18, 31, v2
	v_cmp_eq_u32_e32 vcc, 31, v18
	s_movk_i32 s5, 0x140
	s_mov_b32 s4, 0
	v_cndmask_b32_e64 v3, 0, 1.0, vcc
	s_waitcnt lgkmcnt(11)
	v_fma_f32 v2, v3, v155, 0
	ds_read_b128 v[152:155], v0 offset:2896
	v_cndmask_b32_e64 v2, 0, -v2, vcc
	v_cmp_ne_u32_e32 vcc, 30, v18
	s_nop 1
	v_cndmask_b32_e32 v2, 1.0, v2, vcc
	s_nop 0
	v_cmp_lt_u32_e32 vcc, 29, v18
	s_waitcnt lgkmcnt(11)
	v_pk_mul_f32 v[12:13], v[2:3], v[150:151]
	ds_read_b128 v[196:199], v0 offset:2912
	s_nop 0
	v_add_f32_e32 v12, 0, v12
	v_add_f32_e32 v12, v13, v12
	v_cndmask_b32_e64 v12, 0, -v12, vcc
	v_cmp_ne_u32_e32 vcc, 29, v18
	s_nop 1
	v_cndmask_b32_e32 v13, 1.0, v12, vcc
	s_nop 0
	v_cmp_lt_u32_e32 vcc, 28, v18
	s_waitcnt lgkmcnt(11)
	v_fma_f32 v12, v13, v157, 0
	ds_read_b128 v[200:203], v0 offset:2928
	v_pk_mul_f32 v[14:15], v[2:3], v[158:159]
	s_nop 0
	v_add_f32_e32 v12, v14, v12
	v_add_f32_e32 v12, v15, v12
	v_cndmask_b32_e64 v12, 0, -v12, vcc
	v_cmp_ne_u32_e32 vcc, 28, v18
	s_nop 1
	v_cndmask_b32_e32 v12, 1.0, v12, vcc
	s_nop 0
	v_cmp_lt_u32_e32 vcc, 27, v18
	s_waitcnt lgkmcnt(11)
	v_pk_mul_f32 v[14:15], v[12:13], v[160:161]
	ds_read_b128 v[156:159], v0 offset:2768
	s_nop 0
	v_add_f32_e32 v14, 0, v14
	v_pk_mul_f32 v[16:17], v[2:3], v[162:163]
	v_add_f32_e32 v14, v15, v14
	v_add_f32_e32 v14, v16, v14
	v_add_f32_e32 v14, v17, v14
	v_cndmask_b32_e64 v14, 0, -v14, vcc
	v_cmp_ne_u32_e32 vcc, 27, v18
	s_nop 1
	v_cndmask_b32_e32 v15, 1.0, v14, vcc
	s_nop 0
	s_nop 0
	v_cmp_lt_u32_e32 vcc, 26, v18
	s_waitcnt lgkmcnt(11)
	v_fma_f32 v14, v15, v167, 0
	ds_read_b128 v[160:163], v0 offset:2784
	s_waitcnt lgkmcnt(11)
	v_pk_mul_f32 v[16:17], v[12:13], v[168:169]
	ds_read_b128 v[164:167], v0 offset:2800
	v_pk_mul_f32 v[20:21], v[2:3], v[170:171]
	v_add_f32_e32 v14, v14, v16
	v_add_f32_e32 v14, v17, v14
	v_add_f32_e32 v14, v20, v14
	v_add_f32_e32 v14, v21, v14
	v_cndmask_b32_e64 v14, 0, -v14, vcc
	v_cmp_ne_u32_e32 vcc, 26, v18
	s_nop 1
	v_cndmask_b32_e32 v14, 1.0, v14, vcc
	s_nop 0
	s_nop 0
	v_cmp_lt_u32_e32 vcc, 25, v18
	s_waitcnt lgkmcnt(11)
	v_pk_mul_f32 v[16:17], v[14:15], v[172:173]
	ds_read_b128 v[168:171], v0 offset:2640
	s_nop 0
	v_add_f32_e32 v16, 0, v16
	s_waitcnt lgkmcnt(11)
	v_pk_mul_f32 v[20:21], v[12:13], v[176:177]
	ds_read_b128 v[172:175], v0 offset:2656
	v_add_f32_e32 v16, v17, v16
	v_add_f32_e32 v16, v20, v16
	v_pk_mul_f32 v[22:23], v[2:3], v[178:179]
	v_add_f32_e32 v16, v21, v16
	v_add_f32_e32 v16, v22, v16
	v_add_f32_e32 v16, v23, v16
	v_cndmask_b32_e64 v16, 0, -v16, vcc
	v_cmp_ne_u32_e32 vcc, 25, v18
	s_nop 1
	v_cndmask_b32_e32 v17, 1.0, v16, vcc
	s_nop 0
	s_nop 0
	v_cmp_lt_u32_e32 vcc, 24, v18
	s_waitcnt lgkmcnt(11)
	v_fma_f32 v16, v17, v181, 0
	ds_read_b128 v[176:179], v0 offset:2672
	v_pk_mul_f32 v[20:21], v[14:15], v[182:183]
	s_waitcnt lgkmcnt(11)
	v_pk_mul_f32 v[22:23], v[12:13], v[184:185]
	ds_read_b128 v[180:183], v0 offset:2512
	v_add_f32_e32 v16, v20, v16
	v_add_f32_e32 v16, v21, v16
	v_add_f32_e32 v16, v22, v16
	v_pk_mul_f32 v[24:25], v[2:3], v[186:187]
	v_add_f32_e32 v16, v23, v16
	v_add_f32_e32 v16, v24, v16
	v_add_f32_e32 v16, v25, v16
	v_cndmask_b32_e64 v16, 0, -v16, vcc
	v_cmp_ne_u32_e32 vcc, 24, v18
	s_nop 1
	v_cndmask_b32_e32 v16, 1.0, v16, vcc
	s_nop 0
	s_nop 0
	v_cmp_lt_u32_e32 vcc, 23, v18
	s_waitcnt lgkmcnt(11)
	v_pk_mul_f32 v[20:21], v[16:17], v[188:189]
	ds_read_b128 v[184:187], v0 offset:2528
	s_nop 0
	v_add_f32_e32 v19, 0, v20
	v_pk_mul_f32 v[22:23], v[14:15], v[190:191]
	v_add_f32_e32 v19, v21, v19
	v_add_f32_e32 v19, v22, v19
	s_waitcnt lgkmcnt(11)
	v_pk_mul_f32 v[24:25], v[12:13], v[192:193]
	ds_read_b128 v[188:191], v0 offset:2544
	v_add_f32_e32 v19, v23, v19
	v_add_f32_e32 v19, v24, v19
	v_add_f32_e32 v19, v25, v19
	v_pk_mul_f32 v[20:21], v[2:3], v[194:195]
	s_nop 0
	v_add_f32_e32 v19, v20, v19
	v_add_f32_e32 v19, v21, v19
	v_cndmask_b32_e64 v19, 0, -v19, vcc
	v_cmp_ne_u32_e32 vcc, 23, v18
	s_nop 1
	v_cndmask_b32_e32 v19, 1.0, v19, vcc
	s_nop 0
	s_nop 0
	s_nop 0
	v_cmp_lt_u32_e32 vcc, 22, v18
	s_waitcnt lgkmcnt(11)
	v_fma_f32 v22, v19, v155, 0
	ds_read_b128 v[152:155], v0 offset:2368
	s_waitcnt lgkmcnt(11)
	v_pk_mul_f32 v[20:21], v[16:17], v[196:197]
	ds_read_b128 v[192:195], v0 offset:2384
	s_nop 0
	v_add_f32_e32 v20, v22, v20
	v_add_f32_e32 v22, v21, v20
	v_pk_mul_f32 v[20:21], v[14:15], v[198:199]
	s_nop 0
	v_add_f32_e32 v20, v20, v22
	v_add_f32_e32 v22, v21, v20
	s_waitcnt lgkmcnt(11)
	v_pk_mul_f32 v[20:21], v[12:13], v[200:201]
	ds_read_b128 v[196:199], v0 offset:2400
	s_nop 0
	v_add_f32_e32 v20, v20, v22
	v_add_f32_e32 v22, v21, v20
	v_pk_mul_f32 v[20:21], v[2:3], v[202:203]
	s_nop 0
	v_add_f32_e32 v20, v20, v22
	v_add_f32_e32 v20, v21, v20
	v_cndmask_b32_e64 v20, 0, -v20, vcc
	v_cmp_ne_u32_e32 vcc, 22, v18
	s_nop 1
	v_cndmask_b32_e32 v20, 1.0, v20, vcc
	s_nop 0
	s_nop 0
	s_nop 0
	v_cmp_lt_u32_e32 vcc, 21, v18
	s_waitcnt lgkmcnt(11)
	v_fma_f32 v21, v20, v158, 0
	ds_read_b128 v[200:203], v0 offset:2416
	v_fmac_f32_e32 v21, v19, v159
	s_waitcnt lgkmcnt(11)
; #define LAS __attribute__((address_space(3)))
; __device__ __forceinline__ void rwkv_phaseA(const Ctx& F, LAS unsigned char* W, unsigned char* X, int b, int h, int c) {
;     ...
;         for (int s = 30; s >= 0; --s) {
;             float acc = 0.f;
; #pragma unroll
;             for (int j4 = (s + 1) / 4; j4 < 8; ++j4) { const f32x4 mrow = *(const LAS f32x4*)(W + RA_ZLO + (s * 32 + 4 * j4) * 4);
; #pragma unroll
;                 for (int e = 0; e < 4; ++e) if (4 * j4 + e > s) acc += mrow[e] * x[4 * j4 + e]; }
;             x[s] = (s == tc) ? 1.f : ((s < tc) ? -acc : 0.f);
;             asm volatile("" : "+v"(x[s]) :: "memory");
;         }
	v_pk_mul_f32 v[22:23], v[16:17], v[160:161]
	ds_read_b128 v[156:159], v0 offset:2240
	s_nop 0
	v_add_f32_e32 v21, v22, v21
	v_add_f32_e32 v21, v23, v21
	v_pk_mul_f32 v[22:23], v[14:15], v[162:163]
	s_nop 0
	v_add_f32_e32 v21, v22, v21
	v_add_f32_e32 v21, v23, v21
	s_waitcnt lgkmcnt(11)
	v_pk_mul_f32 v[22:23], v[12:13], v[164:165]
	ds_read_b128 v[160:163], v0 offset:2256
	s_nop 0
	v_add_f32_e32 v21, v22, v21
	v_add_f32_e32 v21, v23, v21
	v_pk_mul_f32 v[22:23], v[2:3], v[166:167]
	s_nop 0
	v_add_f32_e32 v21, v22, v21
	v_add_f32_e32 v21, v23, v21
	v_cndmask_b32_e64 v21, 0, -v21, vcc
	v_cmp_ne_u32_e32 vcc, 21, v18
	s_nop 1
	v_cndmask_b32_e32 v21, 1.0, v21, vcc
	s_nop 0
	s_nop 0
	s_nop 0
	v_cmp_lt_u32_e32 vcc, 20, v18
	s_waitcnt lgkmcnt(11)
	v_fma_f32 v34, v21, v169, 0
	ds_read_b128 v[164:167], v0 offset:2272
	v_fmac_f32_e32 v34, v20, v170
	v_fmac_f32_e32 v34, v19, v171
	s_waitcnt lgkmcnt(11)
	v_pk_mul_f32 v[22:23], v[16:17], v[172:173]
	ds_read_b128 v[168:171], v0 offset:2288
	s_nop 0
	v_add_f32_e32 v22, v22, v34
	v_add_f32_e32 v24, v23, v22
	v_pk_mul_f32 v[22:23], v[14:15], v[174:175]
	s_nop 0
	v_add_f32_e32 v22, v22, v24
	v_add_f32_e32 v24, v23, v22
	s_waitcnt lgkmcnt(11)
	v_pk_mul_f32 v[22:23], v[12:13], v[176:177]
	ds_read_b128 v[172:175], v0 offset:2112
	s_nop 0
	v_add_f32_e32 v22, v22, v24
	v_add_f32_e32 v24, v23, v22
	v_pk_mul_f32 v[22:23], v[2:3], v[178:179]
	s_nop 0
	v_add_f32_e32 v22, v22, v24
	v_add_f32_e32 v22, v23, v22
	v_cndmask_b32_e64 v22, 0, -v22, vcc
	v_cmp_ne_u32_e32 vcc, 20, v18
	s_nop 1
	v_cndmask_b32_e32 v22, 1.0, v22, vcc
	s_nop 0
	s_nop 0
	s_nop 0
	v_cmp_lt_u32_e32 vcc, 19, v18
	s_waitcnt lgkmcnt(11)
	v_fma_f32 v23, v22, v180, 0
	ds_read_b128 v[176:179], v0 offset:2128
	v_fmac_f32_e32 v23, v21, v181
	v_fmac_f32_e32 v23, v20, v182
	v_fmac_f32_e32 v23, v19, v183
	s_waitcnt lgkmcnt(11)
	v_pk_mul_f32 v[24:25], v[16:17], v[184:185]
	ds_read_b128 v[180:183], v0 offset:2144
	s_nop 0
	v_add_f32_e32 v23, v24, v23
	v_add_f32_e32 v23, v25, v23
	v_pk_mul_f32 v[24:25], v[14:15], v[186:187]
	s_nop 0
	v_add_f32_e32 v23, v24, v23
	v_add_f32_e32 v23, v25, v23
	s_waitcnt lgkmcnt(11)
	v_pk_mul_f32 v[24:25], v[12:13], v[188:189]
	ds_read_b128 v[184:187], v0 offset:2160
	s_nop 0
	v_add_f32_e32 v23, v24, v23
	v_add_f32_e32 v23, v25, v23
	v_pk_mul_f32 v[24:25], v[2:3], v[190:191]
	s_nop 0
	v_add_f32_e32 v23, v24, v23
	v_add_f32_e32 v23, v25, v23
	v_cndmask_b32_e64 v23, 0, -v23, vcc
	v_cmp_ne_u32_e32 vcc, 19, v18
	s_nop 1
	v_cndmask_b32_e32 v23, 1.0, v23, vcc
	s_nop 0
	s_nop 0
	s_nop 0
	s_nop 0
	v_cmp_lt_u32_e32 vcc, 18, v18
	s_waitcnt lgkmcnt(11)
	v_fma_f32 v26, v23, v155, 0
	ds_read_b128 v[152:155], v0 offset:1984
	s_waitcnt lgkmcnt(11)
	v_fmac_f32_e32 v26, v22, v192
	ds_read_b128 v[188:191], v0 offset:2000
	v_fmac_f32_e32 v26, v21, v193
	v_fmac_f32_e32 v26, v20, v194
	v_fmac_f32_e32 v26, v19, v195
	s_waitcnt lgkmcnt(11)
	v_pk_mul_f32 v[24:25], v[16:17], v[196:197]
	ds_read_b128 v[192:195], v0 offset:2016
	s_nop 0
	v_add_f32_e32 v24, v24, v26
	v_add_f32_e32 v26, v25, v24
	v_pk_mul_f32 v[24:25], v[14:15], v[198:199]
	s_nop 0
	v_add_f32_e32 v24, v24, v26
	v_add_f32_e32 v26, v25, v24
	s_waitcnt lgkmcnt(11)
	v_pk_mul_f32 v[24:25], v[12:13], v[200:201]
	ds_read_b128 v[196:199], v0 offset:2032
	s_nop 0
	v_add_f32_e32 v24, v24, v26
	v_add_f32_e32 v26, v25, v24
	v_pk_mul_f32 v[24:25], v[2:3], v[202:203]
	s_nop 0
	v_add_f32_e32 v24, v24, v26
	v_add_f32_e32 v24, v25, v24
	v_cndmask_b32_e64 v24, 0, -v24, vcc
	v_cmp_ne_u32_e32 vcc, 18, v18
	s_nop 1
	v_cndmask_b32_e32 v24, 1.0, v24, vcc
	s_nop 0
	s_nop 0
	s_nop 0
	s_nop 0
	v_cmp_lt_u32_e32 vcc, 17, v18
	s_waitcnt lgkmcnt(11)
	v_fma_f32 v25, v24, v158, 0
	ds_read_b128 v[200:203], v0 offset:1840
	v_fmac_f32_e32 v25, v23, v159
	s_waitcnt lgkmcnt(11)
	v_fmac_f32_e32 v25, v22, v160
	ds_read_b128 v[156:159], v0 offset:1856
	v_fmac_f32_e32 v25, v21, v161
	v_fmac_f32_e32 v25, v20, v162
	v_fmac_f32_e32 v25, v19, v163
	s_waitcnt lgkmcnt(11)
	v_pk_mul_f32 v[26:27], v[16:17], v[164:165]
	ds_read_b128 v[160:163], v0 offset:1872
	s_nop 0
	v_add_f32_e32 v25, v26, v25
	v_add_f32_e32 v25, v27, v25
	v_pk_mul_f32 v[26:27], v[14:15], v[166:167]
	s_nop 0
	v_add_f32_e32 v25, v26, v25
	v_add_f32_e32 v25, v27, v25
	s_waitcnt lgkmcnt(11)
	v_pk_mul_f32 v[26:27], v[12:13], v[168:169]
	ds_read_b128 v[164:167], v0 offset:1888
	s_nop 0
	v_add_f32_e32 v25, v26, v25
	v_add_f32_e32 v25, v27, v25
	v_pk_mul_f32 v[26:27], v[2:3], v[170:171]
	s_nop 0
	v_add_f32_e32 v25, v26, v25
	v_add_f32_e32 v25, v27, v25
	v_cndmask_b32_e64 v25, 0, -v25, vcc
	v_cmp_ne_u32_e32 vcc, 17, v18
	s_nop 1
	v_cndmask_b32_e32 v25, 1.0, v25, vcc
	s_nop 0
	s_nop 0
	s_nop 0
	s_nop 0
	v_cmp_lt_u32_e32 vcc, 16, v18
	s_waitcnt lgkmcnt(11)
	v_fma_f32 v42, v25, v173, 0
	ds_read_b128 v[168:171], v0 offset:1904
	v_fmac_f32_e32 v42, v24, v174
	v_fmac_f32_e32 v42, v23, v175
	s_waitcnt lgkmcnt(11)
	v_fmac_f32_e32 v42, v22, v176
	ds_read_b128 v[172:175], v0 offset:1712
	v_fmac_f32_e32 v42, v21, v177
	v_fmac_f32_e32 v42, v20, v178
	v_fmac_f32_e32 v42, v19, v179
	s_waitcnt lgkmcnt(11)
	v_pk_mul_f32 v[26:27], v[16:17], v[180:181]
	ds_read_b128 v[176:179], v0 offset:1728
	s_nop 0
	v_add_f32_e32 v26, v26, v42
	v_add_f32_e32 v28, v27, v26
	v_pk_mul_f32 v[26:27], v[14:15], v[182:183]
	s_nop 0
	v_add_f32_e32 v26, v26, v28
	v_add_f32_e32 v28, v27, v26
	s_waitcnt lgkmcnt(11)
	v_pk_mul_f32 v[26:27], v[12:13], v[184:185]
	ds_read_b128 v[180:183], v0 offset:1744
	s_nop 0
	v_add_f32_e32 v26, v26, v28
	v_add_f32_e32 v28, v27, v26
	v_pk_mul_f32 v[26:27], v[2:3], v[186:187]
	s_nop 0
	v_add_f32_e32 v26, v26, v28
	v_add_f32_e32 v26, v27, v26
	v_cndmask_b32_e64 v26, 0, -v26, vcc
	v_cmp_ne_u32_e32 vcc, 16, v18
	s_nop 1
	v_cndmask_b32_e32 v26, 1.0, v26, vcc
	s_nop 0
	s_nop 0
	s_nop 0
	s_nop 0
	v_cmp_lt_u32_e32 vcc, 15, v18
	s_waitcnt lgkmcnt(11)
; #define LAS __attribute__((address_space(3)))
; __device__ __forceinline__ void rwkv_phaseA(const Ctx& F, LAS unsigned char* W, unsigned char* X, int b, int h, int c) {
;     ...
;         for (int s = 30; s >= 0; --s) {
;             float acc = 0.f;
; #pragma unroll
;             for (int j4 = (s + 1) / 4; j4 < 8; ++j4) { const f32x4 mrow = *(const LAS f32x4*)(W + RA_ZLO + (s * 32 + 4 * j4) * 4);
; #pragma unroll
;                 for (int e = 0; e < 4; ++e) if (4 * j4 + e > s) acc += mrow[e] * x[4 * j4 + e]; }
;             x[s] = (s == tc) ? 1.f : ((s < tc) ? -acc : 0.f);
;             asm volatile("" : "+v"(x[s]) :: "memory");
;         }
	v_fma_f32 v27, v26, v152, 0
	ds_read_b128 v[184:187], v0 offset:1760
	v_fmac_f32_e32 v27, v25, v153
	v_fmac_f32_e32 v27, v24, v154
	v_fmac_f32_e32 v27, v23, v155
	s_waitcnt lgkmcnt(11)
	v_fmac_f32_e32 v27, v22, v188
	ds_read_b128 v[152:155], v0 offset:1776
	v_fmac_f32_e32 v27, v21, v189
	v_fmac_f32_e32 v27, v20, v190
	v_fmac_f32_e32 v27, v19, v191
	s_waitcnt lgkmcnt(11)
	v_pk_mul_f32 v[28:29], v[16:17], v[192:193]
	ds_read_b128 v[188:191], v0 offset:1584
	s_nop 0
	v_add_f32_e32 v27, v28, v27
	v_add_f32_e32 v27, v29, v27
	v_pk_mul_f32 v[28:29], v[14:15], v[194:195]
	s_nop 0
	v_add_f32_e32 v27, v28, v27
	v_add_f32_e32 v27, v29, v27
	s_waitcnt lgkmcnt(11)
	v_pk_mul_f32 v[28:29], v[12:13], v[196:197]
	ds_read_b128 v[192:195], v0 offset:1600
	s_nop 0
	v_add_f32_e32 v27, v28, v27
	v_add_f32_e32 v27, v29, v27
	v_pk_mul_f32 v[28:29], v[2:3], v[198:199]
	s_nop 0
	v_add_f32_e32 v27, v28, v27
	v_add_f32_e32 v27, v29, v27
	v_cndmask_b32_e64 v27, 0, -v27, vcc
	v_cmp_ne_u32_e32 vcc, 15, v18
	s_nop 1
	v_cndmask_b32_e32 v27, 1.0, v27, vcc
	s_nop 0
	s_nop 0
	s_nop 0
	s_nop 0
	v_cmp_lt_u32_e32 vcc, 14, v18
	s_waitcnt lgkmcnt(11)
	v_fma_f32 v28, v27, v203, 0
	ds_read_b128 v[196:199], v0 offset:1616
	s_waitcnt lgkmcnt(11)
	v_fmac_f32_e32 v28, v26, v156
	ds_read_b128 v[200:203], v0 offset:1632
	v_fmac_f32_e32 v28, v25, v157
	v_fmac_f32_e32 v28, v24, v158
	v_fmac_f32_e32 v28, v23, v159
	s_waitcnt lgkmcnt(11)
	v_fmac_f32_e32 v28, v22, v160
	ds_read_b128 v[156:159], v0 offset:1648
	v_fmac_f32_e32 v28, v21, v161
	v_fmac_f32_e32 v28, v20, v162
	v_fmac_f32_e32 v28, v19, v163
	s_waitcnt lgkmcnt(11)
	v_pk_mul_f32 v[32:33], v[16:17], v[164:165]
	ds_read_b128 v[160:163], v0 offset:1456
	s_nop 0
	v_add_f32_e32 v32, v32, v28
	s_nop 0
	v_add_f32_e32 v34, v33, v32
	v_pk_mul_f32 v[32:33], v[14:15], v[166:167]
	s_waitcnt lgkmcnt(11)
	v_pk_mul_f32 v[28:29], v[12:13], v[168:169]
	ds_read_b128 v[164:167], v0 offset:1472
	v_add_f32_e32 v32, v32, v34
	v_add_f32_e32 v32, v33, v32
	v_add_f32_e32 v28, v28, v32
	v_add_f32_e32 v32, v29, v28
	v_pk_mul_f32 v[28:29], v[2:3], v[170:171]
	s_nop 0
	v_add_f32_e32 v28, v28, v32
	v_add_f32_e32 v28, v29, v28
	v_cndmask_b32_e64 v28, 0, -v28, vcc
	v_cmp_ne_u32_e32 vcc, 14, v18
	s_nop 1
	v_cndmask_b32_e32 v28, 1.0, v28, vcc
	s_nop 0
	s_nop 0
	s_nop 0
	s_nop 0
	v_cmp_lt_u32_e32 vcc, 13, v18
	s_waitcnt lgkmcnt(11)
	v_fma_f32 v29, v28, v174, 0
	ds_read_b128 v[168:171], v0 offset:1488
	v_fmac_f32_e32 v29, v27, v175
	s_waitcnt lgkmcnt(11)
	v_fmac_f32_e32 v29, v26, v176
	ds_read_b128 v[172:175], v0 offset:1504
	v_fmac_f32_e32 v29, v25, v177
	v_fmac_f32_e32 v29, v24, v178
	v_fmac_f32_e32 v29, v23, v179
	s_waitcnt lgkmcnt(11)
	v_fmac_f32_e32 v29, v22, v180
	ds_read_b128 v[176:179], v0 offset:1520
	v_fmac_f32_e32 v29, v21, v181
	v_fmac_f32_e32 v29, v20, v182
	s_nop 0
	v_fmac_f32_e32 v29, v19, v183
	s_waitcnt lgkmcnt(11)
	v_pk_mul_f32 v[34:35], v[16:17], v[184:185]
	ds_read_b128 v[180:183], v0 offset:1312
	s_waitcnt lgkmcnt(11)
	v_pk_mul_f32 v[30:31], v[12:13], v[152:153]
	ds_read_b128 v[204:207], v0 offset:1328
	v_add_f32_e32 v29, v34, v29
	v_add_f32_e32 v29, v35, v29
	v_pk_mul_f32 v[34:35], v[14:15], v[186:187]
	s_nop 0
	v_add_f32_e32 v29, v34, v29
	v_add_f32_e32 v29, v35, v29
	v_add_f32_e32 v29, v30, v29
	v_add_f32_e32 v29, v31, v29
	v_pk_mul_f32 v[30:31], v[2:3], v[154:155]
	s_nop 0
	v_add_f32_e32 v29, v30, v29
	v_add_f32_e32 v29, v31, v29
	v_cndmask_b32_e64 v29, 0, -v29, vcc
	v_cmp_ne_u32_e32 vcc, 13, v18
	s_nop 1
	v_cndmask_b32_e32 v29, 1.0, v29, vcc
	s_nop 0
	s_nop 0
	s_nop 0
	s_nop 0
	v_cmp_lt_u32_e32 vcc, 12, v18
	s_waitcnt lgkmcnt(11)
	v_fma_f32 v30, v29, v189, 0
	ds_read_b128 v[152:155], v0 offset:1344
	v_fmac_f32_e32 v30, v28, v190
	v_fmac_f32_e32 v30, v27, v191
	s_waitcnt lgkmcnt(11)
	v_fmac_f32_e32 v30, v26, v192
	ds_read_b128 v[184:187], v0 offset:1360
	v_fmac_f32_e32 v30, v25, v193
	v_fmac_f32_e32 v30, v24, v194
	v_fmac_f32_e32 v30, v23, v195
	s_waitcnt lgkmcnt(11)
	v_fmac_f32_e32 v30, v22, v196
	ds_read_b128 v[188:191], v0 offset:1376
	v_fmac_f32_e32 v30, v21, v197
	v_fmac_f32_e32 v30, v20, v198
	v_fmac_f32_e32 v30, v19, v199
	s_waitcnt lgkmcnt(11)
	v_pk_mul_f32 v[34:35], v[16:17], v[200:201]
	ds_read_b128 v[192:195], v0 offset:1392
	s_nop 0
	v_add_f32_e32 v34, v34, v30
	s_nop 0
	v_add_f32_e32 v36, v35, v34
	v_pk_mul_f32 v[34:35], v[14:15], v[202:203]
	s_waitcnt lgkmcnt(11)
	v_pk_mul_f32 v[30:31], v[12:13], v[156:157]
	ds_read_b128 v[196:199], v0 offset:1184
	v_add_f32_e32 v34, v34, v36
	v_add_f32_e32 v34, v35, v34
	v_add_f32_e32 v30, v30, v34
	v_add_f32_e32 v34, v31, v30
	v_pk_mul_f32 v[30:31], v[2:3], v[158:159]
	s_nop 0
	v_add_f32_e32 v30, v30, v34
	v_add_f32_e32 v30, v31, v30
	v_cndmask_b32_e64 v30, 0, -v30, vcc
	v_cmp_ne_u32_e32 vcc, 12, v18
	s_nop 1
	v_cndmask_b32_e32 v30, 1.0, v30, vcc
	s_nop 0
	s_nop 0
	s_nop 0
	s_nop 0
	v_cmp_lt_u32_e32 vcc, 11, v18
	s_waitcnt lgkmcnt(11)
	v_fma_f32 v31, v30, v160, 0
	ds_read_b128 v[156:159], v0 offset:1200
	v_fmac_f32_e32 v31, v29, v161
	v_fmac_f32_e32 v31, v28, v162
	v_fmac_f32_e32 v31, v27, v163
	s_waitcnt lgkmcnt(11)
	v_fmac_f32_e32 v31, v26, v164
	ds_read_b128 v[160:163], v0 offset:1216
	v_fmac_f32_e32 v31, v25, v165
	v_fmac_f32_e32 v31, v24, v166
	v_fmac_f32_e32 v31, v23, v167
	s_waitcnt lgkmcnt(11)
	v_fmac_f32_e32 v31, v22, v168
	ds_read_b128 v[164:167], v0 offset:1232
	v_fmac_f32_e32 v31, v21, v169
	v_fmac_f32_e32 v31, v20, v170
	s_nop 0
	v_fmac_f32_e32 v31, v19, v171
	s_waitcnt lgkmcnt(11)
	v_pk_mul_f32 v[36:37], v[16:17], v[172:173]
	ds_read_b128 v[168:171], v0 offset:1248
	s_waitcnt lgkmcnt(11)
; #define LAS __attribute__((address_space(3)))
; __device__ __forceinline__ void rwkv_phaseA(const Ctx& F, LAS unsigned char* W, unsigned char* X, int b, int h, int c) {
;     ...
; #pragma unroll
;         for (int s = 30; s >= 0; --s) {
;             float acc = 0.f;
; #pragma unroll
;             for (int j4 = (s + 1) / 4; j4 < 8; ++j4) { const f32x4 mrow = *(const LAS f32x4*)(W + RA_ZLO + (s * 32 + 4 * j4) * 4);
; #pragma unroll
;                 for (int e = 0; e < 4; ++e) if (4 * j4 + e > s) acc += mrow[e] * x[4 * j4 + e]; }
;             x[s] = (s == tc) ? 1.f : ((s < tc) ? -acc : 0.f);
;             asm volatile("" : "+v"(x[s]) :: "memory");
;         }
	v_pk_mul_f32 v[32:33], v[12:13], v[176:177]
	ds_read_b128 v[200:203], v0 offset:1264
	v_add_f32_e32 v31, v36, v31
	v_add_f32_e32 v31, v37, v31
	v_pk_mul_f32 v[36:37], v[14:15], v[174:175]
	s_nop 0
	v_add_f32_e32 v31, v36, v31
	v_add_f32_e32 v31, v37, v31
	v_add_f32_e32 v31, v32, v31
	v_add_f32_e32 v31, v33, v31
	v_pk_mul_f32 v[32:33], v[2:3], v[178:179]
	s_nop 0
	v_add_f32_e32 v31, v32, v31
	v_add_f32_e32 v31, v33, v31
	v_cndmask_b32_e64 v31, 0, -v31, vcc
	v_cmp_ne_u32_e32 vcc, 11, v18
	s_nop 1
	v_cndmask_b32_e32 v31, 1.0, v31, vcc
	s_nop 0
	s_nop 0
	s_nop 0
	s_nop 0
	v_cmp_lt_u32_e32 vcc, 10, v18
	s_waitcnt lgkmcnt(11)
	v_fma_f32 v48, v31, v183, 0
	ds_read_b128 v[172:175], v0 offset:1056
	s_waitcnt lgkmcnt(11)
	v_fmac_f32_e32 v48, v30, v204
	ds_read_b128 v[176:179], v0 offset:1072
	v_fmac_f32_e32 v48, v29, v205
	v_fmac_f32_e32 v48, v28, v206
	v_fmac_f32_e32 v48, v27, v207
	s_waitcnt lgkmcnt(11)
	v_fmac_f32_e32 v48, v26, v152
	ds_read_b128 v[180:183], v0 offset:1088
	v_fmac_f32_e32 v48, v25, v153
	v_fmac_f32_e32 v48, v24, v154
	s_nop 0
	s_nop 0
	v_fmac_f32_e32 v48, v23, v155
	s_waitcnt lgkmcnt(11)
	v_fmac_f32_e32 v48, v22, v184
	ds_read_b128 v[152:155], v0 offset:1104
	v_fmac_f32_e32 v48, v21, v185
	v_fmac_f32_e32 v48, v20, v186
	v_fmac_f32_e32 v48, v19, v187
	s_waitcnt lgkmcnt(11)
	v_pk_mul_f32 v[32:33], v[16:17], v[188:189]
	ds_read_b128 v[184:187], v0 offset:1120
	s_nop 0
	v_add_f32_e32 v32, v32, v48
	v_add_f32_e32 v40, v33, v32
	v_pk_mul_f32 v[32:33], v[14:15], v[190:191]
	s_nop 0
	v_add_f32_e32 v32, v32, v40
	v_add_f32_e32 v34, v33, v32
	s_waitcnt lgkmcnt(11)
	v_pk_mul_f32 v[32:33], v[12:13], v[192:193]
	ds_read_b128 v[188:191], v0 offset:1136
	s_nop 0
	v_add_f32_e32 v32, v32, v34
	v_add_f32_e32 v34, v33, v32
	v_pk_mul_f32 v[32:33], v[2:3], v[194:195]
	s_nop 0
	v_add_f32_e32 v32, v32, v34
	v_add_f32_e32 v32, v33, v32
	v_cndmask_b32_e64 v32, 0, -v32, vcc
	v_cmp_ne_u32_e32 vcc, 10, v18
	s_nop 1
	v_cndmask_b32_e32 v32, 1.0, v32, vcc
	s_nop 0
	s_nop 0
	s_nop 0
	s_nop 0
	v_cmp_lt_u32_e32 vcc, 9, v18
	s_waitcnt lgkmcnt(11)
	v_fma_f32 v33, v32, v198, 0
	ds_read_b128 v[192:195], v0 offset:928
	v_fmac_f32_e32 v33, v31, v199
	s_waitcnt lgkmcnt(11)
	v_fmac_f32_e32 v33, v30, v156
	ds_read_b128 v[196:199], v0 offset:944
	v_fmac_f32_e32 v33, v29, v157
	v_fmac_f32_e32 v33, v28, v158
	v_fmac_f32_e32 v33, v27, v159
	s_waitcnt lgkmcnt(11)
	v_fmac_f32_e32 v33, v26, v160
	ds_read_b128 v[156:159], v0 offset:960
	v_fmac_f32_e32 v33, v25, v161
	v_fmac_f32_e32 v33, v24, v162
	s_nop 0
	s_nop 0
	v_fmac_f32_e32 v33, v23, v163
	s_waitcnt lgkmcnt(11)
	v_fmac_f32_e32 v33, v22, v164
	ds_read_b128 v[160:163], v0 offset:976
	v_fmac_f32_e32 v33, v21, v165
	v_fmac_f32_e32 v33, v20, v166
	v_fmac_f32_e32 v33, v19, v167
	s_waitcnt lgkmcnt(11)
	v_pk_mul_f32 v[34:35], v[16:17], v[168:169]
	ds_read_b128 v[164:167], v0 offset:992
	s_nop 0
	v_add_f32_e32 v33, v34, v33
	v_add_f32_e32 v33, v35, v33
	v_pk_mul_f32 v[34:35], v[14:15], v[170:171]
	s_nop 0
	v_add_f32_e32 v33, v34, v33
	v_add_f32_e32 v33, v35, v33
	s_waitcnt lgkmcnt(11)
	v_pk_mul_f32 v[34:35], v[12:13], v[200:201]
	ds_read_b128 v[168:171], v0 offset:1008
	s_nop 0
	v_add_f32_e32 v33, v34, v33
	v_add_f32_e32 v33, v35, v33
	v_pk_mul_f32 v[34:35], v[2:3], v[202:203]
	s_nop 0
	v_add_f32_e32 v33, v34, v33
	v_add_f32_e32 v33, v35, v33
	v_cndmask_b32_e64 v33, 0, -v33, vcc
	v_cmp_ne_u32_e32 vcc, 9, v18
	s_nop 1
	v_cndmask_b32_e32 v33, 1.0, v33, vcc
	s_nop 0
	s_nop 0
	s_nop 0
	s_nop 0
	v_cmp_lt_u32_e32 vcc, 8, v18
	s_waitcnt lgkmcnt(11)
	v_fma_f32 v50, v33, v173, 0
	ds_read_b128 v[200:203], v0 offset:784
	v_fmac_f32_e32 v50, v32, v174
	v_fmac_f32_e32 v50, v31, v175
	s_waitcnt lgkmcnt(11)
	v_fmac_f32_e32 v50, v30, v176
	ds_read_b128 v[172:175], v0 offset:800
	v_fmac_f32_e32 v50, v29, v177
	v_fmac_f32_e32 v50, v28, v178
	v_fmac_f32_e32 v50, v27, v179
	s_waitcnt lgkmcnt(11)
	v_fmac_f32_e32 v50, v26, v180
	ds_read_b128 v[176:179], v0 offset:816
	v_fmac_f32_e32 v50, v25, v181
	v_fmac_f32_e32 v50, v24, v182
	s_nop 0
	s_nop 0
	v_fmac_f32_e32 v50, v23, v183
	s_waitcnt lgkmcnt(11)
	v_fmac_f32_e32 v50, v22, v152
	ds_read_b128 v[180:183], v0 offset:832
	v_fmac_f32_e32 v50, v21, v153
	v_fmac_f32_e32 v50, v20, v154
	v_fmac_f32_e32 v50, v19, v155
	s_waitcnt lgkmcnt(11)
	v_pk_mul_f32 v[34:35], v[16:17], v[184:185]
	ds_read_b128 v[152:155], v0 offset:848
	s_nop 0
	v_add_f32_e32 v34, v34, v50
	v_add_f32_e32 v42, v35, v34
	v_pk_mul_f32 v[34:35], v[14:15], v[186:187]
	s_nop 0
	v_add_f32_e32 v34, v34, v42
	v_add_f32_e32 v36, v35, v34
	s_waitcnt lgkmcnt(11)
	v_pk_mul_f32 v[34:35], v[12:13], v[188:189]
	ds_read_b128 v[184:187], v0 offset:864
	s_nop 0
	v_add_f32_e32 v34, v34, v36
	v_add_f32_e32 v36, v35, v34
	v_pk_mul_f32 v[34:35], v[2:3], v[190:191]
	s_nop 0
	v_add_f32_e32 v34, v34, v36
	v_add_f32_e32 v34, v35, v34
	v_cndmask_b32_e64 v34, 0, -v34, vcc
	v_cmp_ne_u32_e32 vcc, 8, v18
	s_nop 1
	v_cndmask_b32_e32 v34, 1.0, v34, vcc
	s_nop 0
	s_nop 0
	s_nop 0
	s_nop 0
	v_cmp_lt_u32_e32 vcc, 7, v18
	s_waitcnt lgkmcnt(11)
	v_fma_f32 v35, v34, v192, 0
	ds_read_b128 v[188:191], v0 offset:880
	v_fmac_f32_e32 v35, v33, v193
	v_fmac_f32_e32 v35, v32, v194
	v_fmac_f32_e32 v35, v31, v195
	s_waitcnt lgkmcnt(11)
	v_fmac_f32_e32 v35, v30, v196
	ds_read_b128 v[192:195], v0 offset:656
	v_fmac_f32_e32 v35, v29, v197
	v_fmac_f32_e32 v35, v28, v198
	v_fmac_f32_e32 v35, v27, v199
	s_waitcnt lgkmcnt(11)
	v_fmac_f32_e32 v35, v26, v156
	ds_read_b128 v[196:199], v0 offset:672
	v_fmac_f32_e32 v35, v25, v157
	v_fmac_f32_e32 v35, v24, v158
	s_nop 0
	s_nop 0
	v_fmac_f32_e32 v35, v23, v159
	s_waitcnt lgkmcnt(11)
; #define LAS __attribute__((address_space(3)))
; __device__ __forceinline__ void rwkv_phaseA(const Ctx& F, LAS unsigned char* W, unsigned char* X, int b, int h, int c) {
;     ...
; #pragma unroll
;         for (int s = 30; s >= 0; --s) {
;             float acc = 0.f;
; #pragma unroll
;             for (int j4 = (s + 1) / 4; j4 < 8; ++j4) { const f32x4 mrow = *(const LAS f32x4*)(W + RA_ZLO + (s * 32 + 4 * j4) * 4);
; #pragma unroll
;                 for (int e = 0; e < 4; ++e) if (4 * j4 + e > s) acc += mrow[e] * x[4 * j4 + e]; }
;             x[s] = (s == tc) ? 1.f : ((s < tc) ? -acc : 0.f);
;             asm volatile("" : "+v"(x[s]) :: "memory");
;         }
	v_fmac_f32_e32 v35, v22, v160
	ds_read_b128 v[156:159], v0 offset:688
	v_fmac_f32_e32 v35, v21, v161
	v_fmac_f32_e32 v35, v20, v162
	v_fmac_f32_e32 v35, v19, v163
	s_waitcnt lgkmcnt(11)
	v_pk_mul_f32 v[36:37], v[16:17], v[164:165]
	ds_read_b128 v[160:163], v0 offset:704
	s_nop 0
	v_add_f32_e32 v35, v36, v35
	v_add_f32_e32 v35, v37, v35
	v_pk_mul_f32 v[36:37], v[14:15], v[166:167]
	s_nop 0
	v_add_f32_e32 v35, v36, v35
	v_add_f32_e32 v35, v37, v35
	s_waitcnt lgkmcnt(11)
	v_pk_mul_f32 v[36:37], v[12:13], v[168:169]
	ds_read_b128 v[164:167], v0 offset:720
	s_nop 0
	v_add_f32_e32 v35, v36, v35
	v_add_f32_e32 v35, v37, v35
	v_pk_mul_f32 v[36:37], v[2:3], v[170:171]
	s_nop 0
	v_add_f32_e32 v35, v36, v35
	v_add_f32_e32 v35, v37, v35
	v_cndmask_b32_e64 v35, 0, -v35, vcc
	v_cmp_ne_u32_e32 vcc, 7, v18
	s_nop 1
	v_cndmask_b32_e32 v35, 1.0, v35, vcc
	s_nop 0
	s_nop 0
	s_nop 0
	s_nop 0
	v_cmp_lt_u32_e32 vcc, 6, v18
	s_waitcnt lgkmcnt(11)
	v_fma_f32 v52, v35, v203, 0
	ds_read_b128 v[168:171], v0 offset:736
	s_waitcnt lgkmcnt(11)
	v_fmac_f32_e32 v52, v34, v172
	ds_read_b128 v[200:203], v0 offset:752
	v_fmac_f32_e32 v52, v33, v173
	v_fmac_f32_e32 v52, v32, v174
	v_fmac_f32_e32 v52, v31, v175
	s_waitcnt lgkmcnt(11)
	v_fmac_f32_e32 v52, v30, v176
	ds_read_b128 v[172:175], v0 offset:528
	v_fmac_f32_e32 v52, v29, v177
	v_fmac_f32_e32 v52, v28, v178
	v_fmac_f32_e32 v52, v27, v179
	s_nop 0
	s_nop 0
	s_waitcnt lgkmcnt(11)
	v_fmac_f32_e32 v52, v26, v180
	ds_read_b128 v[176:179], v0 offset:544
	v_fmac_f32_e32 v52, v25, v181
	v_fmac_f32_e32 v52, v24, v182
	v_fmac_f32_e32 v52, v23, v183
	s_waitcnt lgkmcnt(11)
	v_fmac_f32_e32 v52, v22, v152
	ds_read_b128 v[180:183], v0 offset:560
	v_fmac_f32_e32 v52, v21, v153
	v_fmac_f32_e32 v52, v20, v154
	v_fmac_f32_e32 v52, v19, v155
	s_nop 0
	s_waitcnt lgkmcnt(11)
	v_pk_mul_f32 v[40:41], v[16:17], v[184:185]
	ds_read_b128 v[152:155], v0 offset:576
	s_waitcnt lgkmcnt(11)
	v_pk_mul_f32 v[36:37], v[12:13], v[188:189]
	ds_read_b128 v[204:207], v0 offset:592
	v_add_f32_e32 v40, v40, v52
	v_add_f32_e32 v44, v41, v40
	v_pk_mul_f32 v[40:41], v[14:15], v[186:187]
	s_nop 0
	v_add_f32_e32 v40, v40, v44
	v_add_f32_e32 v40, v41, v40
	v_add_f32_e32 v36, v36, v40
	v_add_f32_e32 v40, v37, v36
	v_pk_mul_f32 v[36:37], v[2:3], v[190:191]
	s_nop 0
	v_add_f32_e32 v36, v36, v40
	v_add_f32_e32 v36, v37, v36
	v_cndmask_b32_e64 v36, 0, -v36, vcc
	v_cmp_ne_u32_e32 vcc, 6, v18
	s_nop 1
	v_cndmask_b32_e32 v52, 1.0, v36, vcc
	s_nop 0
	s_nop 0
	s_nop 0
	s_nop 0
	v_cmp_lt_u32_e32 vcc, 5, v18
	s_waitcnt lgkmcnt(11)
	v_fma_f32 v94, v52, v194, 0
	ds_read_b128 v[184:187], v0 offset:608
	v_fmac_f32_e32 v94, v35, v195
	s_waitcnt lgkmcnt(11)
	v_fmac_f32_e32 v94, v34, v196
	ds_read_b128 v[188:191], v0 offset:624
	v_fmac_f32_e32 v94, v33, v197
	v_fmac_f32_e32 v94, v32, v198
	v_fmac_f32_e32 v94, v31, v199
	s_waitcnt lgkmcnt(11)
	v_fmac_f32_e32 v94, v30, v156
	ds_read_b128 v[192:195], v0 offset:400
	v_fmac_f32_e32 v94, v29, v157
	v_fmac_f32_e32 v94, v28, v158
	v_fmac_f32_e32 v94, v27, v159
	s_nop 0
	s_nop 0
	s_waitcnt lgkmcnt(11)
	v_fmac_f32_e32 v94, v26, v160
	ds_read_b128 v[156:159], v0 offset:416
	v_fmac_f32_e32 v94, v25, v161
	v_fmac_f32_e32 v94, v24, v162
	v_fmac_f32_e32 v94, v23, v163
	s_waitcnt lgkmcnt(11)
	v_fmac_f32_e32 v94, v22, v164
	ds_read_b128 v[160:163], v0 offset:432
	v_fmac_f32_e32 v94, v21, v165
	v_fmac_f32_e32 v94, v20, v166
	v_fmac_f32_e32 v94, v19, v167
	s_nop 0
	s_waitcnt lgkmcnt(11)
	v_pk_mul_f32 v[40:41], v[16:17], v[168:169]
	ds_read_b128 v[164:167], v0 offset:448
	s_waitcnt lgkmcnt(11)
	v_pk_mul_f32 v[36:37], v[12:13], v[200:201]
	ds_read_b128 v[196:199], v0 offset:464
	v_add_f32_e32 v40, v40, v94
	v_add_f32_e32 v44, v41, v40
	v_pk_mul_f32 v[40:41], v[14:15], v[170:171]
	s_nop 0
	v_add_f32_e32 v40, v40, v44
	v_add_f32_e32 v40, v41, v40
	v_add_f32_e32 v36, v36, v40
	v_add_f32_e32 v40, v37, v36
	v_pk_mul_f32 v[36:37], v[2:3], v[202:203]
	s_nop 0
	v_add_f32_e32 v36, v36, v40
	v_add_f32_e32 v36, v37, v36
	v_cndmask_b32_e64 v36, 0, -v36, vcc
	v_cmp_ne_u32_e32 vcc, 5, v18
	s_nop 1
	v_cndmask_b32_e32 v94, 1.0, v36, vcc
	s_nop 0
	s_nop 0
	s_nop 0
	s_nop 0
	v_cmp_lt_u32_e32 vcc, 4, v18
	s_waitcnt lgkmcnt(11)
	v_fma_f32 v95, v94, v173, 0
	ds_read_b128 v[168:171], v0 offset:480
	v_fmac_f32_e32 v95, v52, v174
	v_fmac_f32_e32 v95, v35, v175
	s_waitcnt lgkmcnt(11)
	v_fmac_f32_e32 v95, v34, v176
	ds_read_b128 v[172:175], v0 offset:496
	v_fmac_f32_e32 v95, v33, v177
	v_fmac_f32_e32 v95, v32, v178
	v_fmac_f32_e32 v95, v31, v179
	s_waitcnt lgkmcnt(11)
	v_fmac_f32_e32 v95, v30, v180
	ds_read_b128 v[176:179], v0 offset:256
	v_fmac_f32_e32 v95, v29, v181
	v_fmac_f32_e32 v95, v28, v182
	v_fmac_f32_e32 v95, v27, v183
	s_nop 0
	s_nop 0
	s_waitcnt lgkmcnt(11)
	v_fmac_f32_e32 v95, v26, v152
	ds_read_b128 v[180:183], v0 offset:272
	v_fmac_f32_e32 v95, v25, v153
	v_fmac_f32_e32 v95, v24, v154
	v_fmac_f32_e32 v95, v23, v155
	s_waitcnt lgkmcnt(11)
	v_fmac_f32_e32 v95, v22, v204
	ds_read_b128 v[152:155], v0 offset:288
	v_fmac_f32_e32 v95, v21, v205
	v_fmac_f32_e32 v95, v20, v206
	v_fmac_f32_e32 v95, v19, v207
	s_nop 0
	s_waitcnt lgkmcnt(11)
	v_pk_mul_f32 v[40:41], v[16:17], v[184:185]
	ds_read_b128 v[200:203], v0 offset:304
	s_waitcnt lgkmcnt(11)
	v_pk_mul_f32 v[36:37], v[12:13], v[188:189]
	ds_read_b128 v[204:207], v0 offset:320
	v_add_f32_e32 v40, v40, v95
	v_add_f32_e32 v44, v41, v40
	v_pk_mul_f32 v[40:41], v[14:15], v[186:187]
	s_nop 0
	v_add_f32_e32 v40, v40, v44
	v_add_f32_e32 v40, v41, v40
	v_add_f32_e32 v36, v36, v40
	v_add_f32_e32 v40, v37, v36
	v_pk_mul_f32 v[36:37], v[2:3], v[190:191]
	s_nop 0
	v_add_f32_e32 v36, v36, v40
	v_add_f32_e32 v36, v37, v36
	v_cndmask_b32_e64 v36, 0, -v36, vcc
	v_cmp_ne_u32_e32 vcc, 4, v18
	s_nop 1
	v_cndmask_b32_e32 v95, 1.0, v36, vcc
	s_nop 0
	s_nop 0
	s_nop 0
	s_nop 0
	v_cmp_lt_u32_e32 vcc, 3, v18
	s_waitcnt lgkmcnt(11)
; #define LAS __attribute__((address_space(3)))
; __device__ __forceinline__ void rwkv_phaseA(const Ctx& F, LAS unsigned char* W, unsigned char* X, int b, int h, int c) {
;     ...
; #pragma unroll
;         for (int s = 30; s >= 0; --s) {
;             float acc = 0.f;
; #pragma unroll
;             for (int j4 = (s + 1) / 4; j4 < 8; ++j4) { const f32x4 mrow = *(const LAS f32x4*)(W + RA_ZLO + (s * 32 + 4 * j4) * 4);
; #pragma unroll
;                 for (int e = 0; e < 4; ++e) if (4 * j4 + e > s) acc += mrow[e] * x[4 * j4 + e]; }
;             x[s] = (s == tc) ? 1.f : ((s < tc) ? -acc : 0.f);
;             asm volatile("" : "+v"(x[s]) :: "memory");
;         }
	v_fma_f32 v96, v95, v192, 0
	ds_read_b128 v[184:187], v0 offset:336
	v_fmac_f32_e32 v96, v94, v193
	v_fmac_f32_e32 v96, v52, v194
	v_fmac_f32_e32 v96, v35, v195
	s_waitcnt lgkmcnt(11)
	v_fmac_f32_e32 v96, v34, v156
	ds_read_b128 v[188:191], v0 offset:352
	v_fmac_f32_e32 v96, v33, v157
	v_fmac_f32_e32 v96, v32, v158
	v_fmac_f32_e32 v96, v31, v159
	s_waitcnt lgkmcnt(11)
	v_fmac_f32_e32 v96, v30, v160
	ds_read_b128 v[156:159], v0 offset:368
	v_fmac_f32_e32 v96, v29, v161
	v_fmac_f32_e32 v96, v28, v162
	v_fmac_f32_e32 v96, v27, v163
	s_nop 0
	s_nop 0
	s_waitcnt lgkmcnt(11)
	v_fmac_f32_e32 v96, v26, v164
	ds_read_b128 v[160:163], v0 offset:128
	v_fmac_f32_e32 v96, v25, v165
	v_fmac_f32_e32 v96, v24, v166
	v_fmac_f32_e32 v96, v23, v167
	s_waitcnt lgkmcnt(11)
	v_fmac_f32_e32 v96, v22, v196
	ds_read_b128 v[164:167], v0 offset:144
	v_fmac_f32_e32 v96, v21, v197
	v_fmac_f32_e32 v96, v20, v198
	v_fmac_f32_e32 v96, v19, v199
	s_nop 0
	s_waitcnt lgkmcnt(11)
	v_pk_mul_f32 v[40:41], v[16:17], v[168:169]
	ds_read_b128 v[192:195], v0 offset:160
	s_waitcnt lgkmcnt(11)
	v_pk_mul_f32 v[36:37], v[12:13], v[172:173]
	ds_read_b128 v[196:199], v0 offset:176
	v_add_f32_e32 v40, v40, v96
	v_add_f32_e32 v44, v41, v40
	v_pk_mul_f32 v[40:41], v[14:15], v[170:171]
	s_nop 0
	v_add_f32_e32 v40, v40, v44
	v_add_f32_e32 v40, v41, v40
	v_add_f32_e32 v36, v36, v40
	v_add_f32_e32 v40, v37, v36
	v_pk_mul_f32 v[36:37], v[2:3], v[174:175]
	s_nop 0
	v_add_f32_e32 v36, v36, v40
	v_add_f32_e32 v36, v37, v36
	v_cndmask_b32_e64 v36, 0, -v36, vcc
	v_cmp_ne_u32_e32 vcc, 3, v18
	s_nop 1
	v_cndmask_b32_e32 v96, 1.0, v36, vcc
	s_nop 0
	s_nop 0
	s_nop 0
	s_nop 0
	v_cmp_lt_u32_e32 vcc, 2, v18
	s_waitcnt lgkmcnt(11)
	v_fma_f32 v97, v96, v179, 0
	ds_read_b128 v[168:171], v0 offset:192
	s_waitcnt lgkmcnt(11)
	v_fmac_f32_e32 v97, v95, v180
	ds_read_b128 v[172:175], v0 offset:208
	v_fmac_f32_e32 v97, v94, v181
	v_fmac_f32_e32 v97, v52, v182
	v_fmac_f32_e32 v97, v35, v183
	s_waitcnt lgkmcnt(11)
	v_fmac_f32_e32 v97, v34, v152
	ds_read_b128 v[176:179], v0 offset:224
	v_fmac_f32_e32 v97, v33, v153
	v_fmac_f32_e32 v97, v32, v154
	v_fmac_f32_e32 v97, v31, v155
	s_nop 0
	s_nop 0
	s_waitcnt lgkmcnt(11)
	v_fmac_f32_e32 v97, v30, v200
	ds_read_b128 v[152:155], v0 offset:240
	v_fmac_f32_e32 v97, v29, v201
	v_fmac_f32_e32 v97, v28, v202
	v_fmac_f32_e32 v97, v27, v203
	s_waitcnt lgkmcnt(11)
	v_fmac_f32_e32 v97, v26, v204
	ds_read_b128 v[180:183], v0
	v_fmac_f32_e32 v97, v25, v205
	v_fmac_f32_e32 v97, v24, v206
	v_fmac_f32_e32 v97, v23, v207
	s_nop 0
	s_waitcnt lgkmcnt(11)
	v_fmac_f32_e32 v97, v22, v184
	ds_read_b128 v[200:203], v0 offset:16
	v_fmac_f32_e32 v97, v21, v185
	v_fmac_f32_e32 v97, v20, v186
	v_fmac_f32_e32 v97, v19, v187
	s_nop 0
	s_waitcnt lgkmcnt(11)
	v_pk_mul_f32 v[36:37], v[16:17], v[188:189]
	ds_read_b128 v[184:187], v0 offset:32
	s_nop 0
	v_add_f32_e32 v36, v36, v97
	v_add_f32_e32 v44, v37, v36
	v_pk_mul_f32 v[36:37], v[14:15], v[190:191]
	s_nop 0
	v_add_f32_e32 v36, v36, v44
	v_add_f32_e32 v38, v37, v36
	s_waitcnt lgkmcnt(11)
	v_pk_mul_f32 v[36:37], v[12:13], v[156:157]
	ds_read_b128 v[188:191], v0 offset:48
	s_nop 0
	v_add_f32_e32 v36, v36, v38
	v_add_f32_e32 v38, v37, v36
	v_pk_mul_f32 v[36:37], v[2:3], v[158:159]
	s_nop 0
	v_add_f32_e32 v36, v36, v38
	v_add_f32_e32 v36, v37, v36
	v_cndmask_b32_e64 v36, 0, -v36, vcc
	v_cmp_ne_u32_e32 vcc, 2, v18
	s_nop 1
	v_cndmask_b32_e32 v97, 1.0, v36, vcc
	s_nop 0
	s_nop 0
	s_nop 0
	s_nop 0
	v_cmp_lt_u32_e32 vcc, 1, v18
	s_waitcnt lgkmcnt(11)
	v_fma_f32 v98, v97, v162, 0
	ds_read_b128 v[156:159], v0 offset:64
	v_fmac_f32_e32 v98, v96, v163
	s_waitcnt lgkmcnt(11)
	v_fmac_f32_e32 v98, v95, v164
	ds_read_b128 v[160:163], v0 offset:80
	v_fmac_f32_e32 v98, v94, v165
	v_fmac_f32_e32 v98, v52, v166
	v_fmac_f32_e32 v98, v35, v167
	s_waitcnt lgkmcnt(11)
; #define LAS __attribute__((address_space(3)))
; __device__ __forceinline__ unsigned pk2(float lo, float hi) { f32x2 v = {lo, hi}; bf16x2_t b = __builtin_convertvector(v, bf16x2_t); return __builtin_bit_cast(unsigned, b); }
; __device__ __forceinline__ void rwkv_phaseA(const Ctx& F, LAS unsigned char* W, unsigned char* X, int b, int h, int c) {
;     ...
; #pragma unroll
;         for (int s = 30; s >= 0; --s) {
;             float acc = 0.f;
; #pragma unroll
;             for (int j4 = (s + 1) / 4; j4 < 8; ++j4) { const f32x4 mrow = *(const LAS f32x4*)(W + RA_ZLO + (s * 32 + 4 * j4) * 4);
; #pragma unroll
;                 for (int e = 0; e < 4; ++e) if (4 * j4 + e > s) acc += mrow[e] * x[4 * j4 + e]; }
;             x[s] = (s == tc) ? 1.f : ((s < tc) ? -acc : 0.f);
;             asm volatile("" : "+v"(x[s]) :: "memory");
;         }
;         asm volatile("s_waitcnt lgkmcnt(0)" ::: "memory");
; #pragma unroll
;         for (int q = 0; q < 4; ++q) *(LAS u32x4*)(W + RA_ZLO + tc * 80 + 16 * q) = (u32x4){pk2(x[8 * q], x[8 * q + 1]), pk2(x[8 * q + 2], x[8 * q + 3]), pk2(x[8 * q + 4], x[8 * q + 5]), pk2(x[8 * q + 6], x[8 * q + 7])};
;     }
;     asm volatile("s_waitcnt lgkmcnt(0)" ::: "memory");
;     {
;         const bf16x8 tb0 = lds16(W + RA_ZLO + i * 80 + 16 * g), tb1 = lds16(W + RA_ZLO + (16 + i) * 80 + 16 * g);
	v_fmac_f32_e32 v98, v34, v192
	ds_read_b128 v[164:167], v0 offset:96
	v_fmac_f32_e32 v98, v33, v193
	v_fmac_f32_e32 v98, v32, v194
	v_fmac_f32_e32 v98, v31, v195
	s_nop 0
	s_nop 0
	s_waitcnt lgkmcnt(11)
	v_fmac_f32_e32 v98, v30, v196
	ds_read_b128 v[192:195], v0 offset:112
	v_fmac_f32_e32 v98, v29, v197
	v_fmac_f32_e32 v98, v28, v198
	v_fmac_f32_e32 v98, v27, v199
	s_waitcnt lgkmcnt(11)
	v_fmac_f32_e32 v98, v26, v168
	v_fmac_f32_e32 v98, v25, v169
	v_fmac_f32_e32 v98, v24, v170
	v_fmac_f32_e32 v98, v23, v171
	s_nop 0
	s_waitcnt lgkmcnt(10)
	v_fmac_f32_e32 v98, v22, v172
	v_fmac_f32_e32 v98, v21, v173
	v_fmac_f32_e32 v98, v20, v174
	v_fmac_f32_e32 v98, v19, v175
	s_nop 0
	s_waitcnt lgkmcnt(9)
	v_pk_mul_f32 v[36:37], v[16:17], v[176:177]
	s_nop 0
	v_add_f32_e32 v36, v36, v98
	v_add_f32_e32 v44, v37, v36
	v_pk_mul_f32 v[36:37], v[14:15], v[178:179]
	s_nop 0
	v_add_f32_e32 v36, v36, v44
	v_add_f32_e32 v38, v37, v36
	s_waitcnt lgkmcnt(8)
	v_pk_mul_f32 v[36:37], v[12:13], v[152:153]
	s_nop 0
	v_add_f32_e32 v36, v36, v38
	v_add_f32_e32 v38, v37, v36
	v_pk_mul_f32 v[36:37], v[2:3], v[154:155]
	s_nop 0
	v_add_f32_e32 v36, v36, v38
	v_add_f32_e32 v36, v37, v36
	v_cndmask_b32_e64 v36, 0, -v36, vcc
	v_cmp_ne_u32_e32 vcc, 1, v18
	s_nop 1
	v_cndmask_b32_e32 v98, 1.0, v36, vcc
	s_nop 0
	s_nop 0
	s_nop 0
	s_nop 0
	v_cmp_ne_u32_e32 vcc, 0, v18
	s_waitcnt lgkmcnt(7)
	v_fma_f32 v99, v98, v181, 0
	v_fmac_f32_e32 v99, v97, v182
	v_fmac_f32_e32 v99, v96, v183
	s_waitcnt lgkmcnt(6)
	v_fmac_f32_e32 v99, v95, v200
	v_fmac_f32_e32 v99, v94, v201
	v_fmac_f32_e32 v99, v52, v202
	v_fmac_f32_e32 v99, v35, v203
	s_waitcnt lgkmcnt(5)
	v_fmac_f32_e32 v99, v34, v184
	v_fmac_f32_e32 v99, v33, v185
	v_fmac_f32_e32 v99, v32, v186
	v_fmac_f32_e32 v99, v31, v187
	s_nop 0
	s_nop 0
	s_waitcnt lgkmcnt(4)
	v_fmac_f32_e32 v99, v30, v188
	v_fmac_f32_e32 v99, v29, v189
	v_fmac_f32_e32 v99, v28, v190
	v_fmac_f32_e32 v99, v27, v191
	s_waitcnt lgkmcnt(3)
	v_fmac_f32_e32 v99, v26, v156
	v_fmac_f32_e32 v99, v25, v157
	v_fmac_f32_e32 v99, v24, v158
	v_fmac_f32_e32 v99, v23, v159
	s_nop 0
	s_waitcnt lgkmcnt(2)
	v_fmac_f32_e32 v99, v22, v160
	v_fmac_f32_e32 v99, v21, v161
	v_fmac_f32_e32 v99, v20, v162
	v_fmac_f32_e32 v99, v19, v163
	s_nop 0
	s_waitcnt lgkmcnt(1)
	v_pk_mul_f32 v[36:37], v[16:17], v[164:165]
	v_mad_u32_u24 v0, v18, s96, v0
	v_add_f32_e32 v36, v36, v99
	v_add_f32_e32 v44, v37, v36
	v_pk_mul_f32 v[36:37], v[14:15], v[166:167]
	v_cvt_pk_bf16_f32 v39, v52, v35
	v_add_f32_e32 v36, v36, v44
	v_add_f32_e32 v38, v37, v36
	s_waitcnt lgkmcnt(0)
	v_pk_mul_f32 v[36:37], v[12:13], v[192:193]
	v_cvt_pk_bf16_f32 v34, v34, v33
	v_add_f32_e32 v36, v36, v38
	v_add_f32_e32 v38, v37, v36
	v_pk_mul_f32 v[36:37], v[2:3], v[194:195]
	v_cvt_pk_bf16_f32 v35, v32, v31
	v_add_f32_e32 v36, v36, v38
	v_add_f32_e32 v36, v37, v36
	v_cndmask_b32_e64 v36, 1.0, -v36, vcc
	v_cvt_pk_bf16_f32 v37, v97, v96
	v_cvt_pk_bf16_f32 v36, v36, v98
	v_cvt_pk_bf16_f32 v38, v95, v94
	s_waitcnt lgkmcnt(0)
	v_mov_b32_e32 v40, v192
	v_mov_b32_e32 v41, v193
	v_mov_b32_e32 v42, v194
	v_mov_b32_e32 v43, v195
	v_mov_b32_e32 v45, v185
	v_mov_b32_e32 v46, v186
	v_mov_b32_e32 v47, v187
	v_mov_b32_e32 v48, v188
	v_mov_b32_e32 v49, v189
	v_mov_b32_e32 v50, v190
	v_mov_b32_e32 v51, v191
	ds_write_b128 v0, v[36:39]
	v_cvt_pk_bf16_f32 v36, v30, v29
	v_cvt_pk_bf16_f32 v37, v28, v27
	v_cvt_pk_bf16_f32 v26, v26, v25
	v_cvt_pk_bf16_f32 v27, v24, v23
	v_cvt_pk_bf16_f32 v28, v22, v21
	v_cvt_pk_bf16_f32 v29, v20, v19
	v_cvt_pk_bf16_f32 v16, v16, v17
	v_cvt_pk_bf16_f32 v17, v14, v15
	v_cvt_pk_bf16_f32 v18, v12, v13
	v_cvt_pk_bf16_f32 v19, v2, v3
	ds_write_b128 v0, v[34:37] offset:16
	ds_write_b128 v0, v[26:29] offset:32
	ds_write_b128 v0, v[16:19] offset:48
	v_add_u32_e32 v2, s43, v58
	s_waitcnt lgkmcnt(0)
	v_add_u32_e32 v0, v2, v59
	v_add_u32_e32 v3, v2, v67
	ds_read_b128 v[12:15], v0
	ds_read_b128 v[16:19], v3
	v_mul_lo_u32 v3, v54, s5
	v_or_b32_e32 v3, v3, v57
	v_add_u32_e32 v3, s43, v3
	v_mov_b32_e32 v20, v53
